# v31 + nt hint on the residual-stream (X, f32) loads of the two EpiResidNorm epilogues
# baseline (speedup 1.0000x reference)
.LBB0_1000:
	s_lshl_b32 s0, s4, 5
	s_lshl_b32 s5, s53, 8
	s_lshl_b32 s1, s8, 8
	s_add_i32 s2, s5, s36
	s_or_b32 s0, s1, s0
	s_cmp_gt_i32 s53, 15
	v_lshl_or_b32 v162, v152, 3, s0
	s_cselect_b32 s0, 0x3000, 0
	s_lshl_b32 s12, s0, 2
	v_readlane_b32 s0, v255, 2
	v_readlane_b32 s1, v255, 3
	s_add_u32 s0, s0, s12
	v_ashrrev_i32_e32 v163, 31, v162
	s_addc_u32 s1, s1, 0
	v_lshlrev_b64 v[146:147], 2, v[162:163]
	v_lshl_add_u64 v[130:131], s[0:1], 0, v[146:147]
	s_movk_i32 s0, 0x4000
	v_or_b32_e32 v148, s2, v148
	v_lshl_add_u64 v[134:135], v[130:131], 0, s[26:27]
	v_add_co_u32_e32 v130, vcc, s0, v130
	v_ashrrev_i32_e32 v149, 31, v148
	v_readlane_b32 s0, v254, 61
	v_lshlrev_b64 v[150:151], 13, v[148:149]
	v_readlane_b32 s1, v254, 62
	v_addc_co_u32_e32 v131, vcc, 0, v131, vcc
	s_nop 0
	v_lshl_add_u64 v[150:151], s[0:1], 0, v[150:151]
	v_lshl_add_u64 v[150:151], v[150:151], 0, v[146:147]
	s_waitcnt vmcnt(0)
	s_barrier
	global_load_dwordx4 v[142:145], v[130:131], off
	global_load_dwordx4 v[138:141], v[134:135], off offset:16
	s_nop 0
	global_load_dwordx4 v[130:133], v[134:135], off offset:528
	s_nop 0
	global_load_dwordx4 v[134:137], v[134:135], off offset:512
	s_nop 0
	s_nop 0
	global_load_dwordx4 v[178:181], v[150:151], off offset:16 nt
	global_load_dwordx4 v[182:185], v[150:151], off nt
	global_load_dwordx4 v[186:189], v[150:151], off offset:528 nt
	global_load_dwordx4 v[190:193], v[150:151], off offset:512 nt
	v_add_co_u32_e32 v164, vcc, 0x20000, v150
	s_nop 1
	v_addc_co_u32_e32 v165, vcc, 0, v151, vcc
	global_load_dwordx4 v[198:201], v[164:165], off offset:16 nt
	global_load_dwordx4 v[202:205], v[164:165], off nt
	global_load_dwordx4 v[206:209], v[164:165], off offset:528 nt
	global_load_dwordx4 v[214:217], v[164:165], off offset:512 nt
	v_add_co_u32_e32 v164, vcc, 0x40000, v150
	s_nop 1
	v_addc_co_u32_e32 v165, vcc, 0, v151, vcc
	global_load_dwordx4 v[218:221], v[164:165], off offset:16 nt
	global_load_dwordx4 v[222:225], v[164:165], off nt
	global_load_dwordx4 v[226:229], v[164:165], off offset:528 nt
	global_load_dwordx4 v[230:233], v[164:165], off offset:512 nt
	v_add_co_u32_e32 v164, vcc, 0x60000, v150
	s_nop 1
	v_addc_co_u32_e32 v165, vcc, 0, v151, vcc
	global_load_dwordx4 v[234:237], v[164:165], off offset:16 nt
	global_load_dwordx4 v[238:241], v[164:165], off nt
	global_load_dwordx4 v[242:245], v[164:165], off offset:528 nt
	global_load_dwordx4 v[154:157], v[164:165], off offset:512 nt
	s_waitcnt vmcnt(15)
	v_pk_fma_f32 v[108:109], v[108:109], v[140:141], v[180:181]
	v_pk_fma_f32 v[106:107], v[106:107], v[138:139], v[178:179]
	v_add_co_u32_e32 v164, vcc, 0x100000, v150
	s_nop 1
	v_addc_co_u32_e32 v165, vcc, 0, v151, vcc
	global_load_dwordx4 v[178:181], v[164:165], off nt
	s_waitcnt vmcnt(15)
	v_pk_fma_f32 v[112:113], v[112:113], v[144:145], v[184:185]
	v_pk_fma_f32 v[110:111], v[110:111], v[142:143], v[182:183]
	global_load_dwordx4 v[182:185], v[164:165], off offset:16 nt
	s_waitcnt vmcnt(15)
	v_pk_fma_f32 v[0:1], v[0:1], v[130:131], v[186:187]
	v_pk_fma_f32 v[2:3], v[2:3], v[132:133], v[188:189]
	global_load_dwordx4 v[186:189], v[164:165], off offset:528 nt
	s_waitcnt vmcnt(15)
	v_pk_fma_f32 v[6:7], v[6:7], v[136:137], v[192:193]
	v_pk_fma_f32 v[4:5], v[4:5], v[134:135], v[190:191]
	global_load_dwordx4 v[190:193], v[164:165], off offset:512 nt
	s_waitcnt vmcnt(15)
	v_pk_fma_f32 v[116:117], v[116:117], v[140:141], v[200:201]
	v_pk_fma_f32 v[114:115], v[114:115], v[138:139], v[198:199]
	v_add_co_u32_e32 v164, vcc, 0x120000, v150
	s_nop 1
	v_addc_co_u32_e32 v165, vcc, 0, v151, vcc
	global_load_dwordx4 v[198:201], v[164:165], off nt
	s_waitcnt vmcnt(15)
	v_pk_fma_f32 v[120:121], v[120:121], v[144:145], v[204:205]
	v_pk_fma_f32 v[118:119], v[118:119], v[142:143], v[202:203]
	global_load_dwordx4 v[202:205], v[164:165], off offset:16 nt
	s_waitcnt vmcnt(15)
	v_pk_fma_f32 v[8:9], v[8:9], v[130:131], v[206:207]
	v_pk_fma_f32 v[10:11], v[10:11], v[132:133], v[208:209]
	global_load_dwordx4 v[206:209], v[164:165], off offset:528 nt
	s_waitcnt vmcnt(15)
	v_pk_fma_f32 v[14:15], v[14:15], v[136:137], v[216:217]
	v_pk_fma_f32 v[12:13], v[12:13], v[134:135], v[214:215]
	global_load_dwordx4 v[214:217], v[164:165], off offset:512 nt
	s_waitcnt vmcnt(15)
	v_pk_fma_f32 v[124:125], v[124:125], v[140:141], v[220:221]
	v_pk_fma_f32 v[122:123], v[122:123], v[138:139], v[218:219]
	v_add_co_u32_e32 v164, vcc, 0x140000, v150
	s_nop 1
	v_addc_co_u32_e32 v165, vcc, 0, v151, vcc
	global_load_dwordx4 v[218:221], v[164:165], off nt
	s_waitcnt vmcnt(15)
	v_pk_fma_f32 v[128:129], v[128:129], v[144:145], v[224:225]
	v_pk_fma_f32 v[126:127], v[126:127], v[142:143], v[222:223]
	global_load_dwordx4 v[222:225], v[164:165], off offset:16 nt
	s_waitcnt vmcnt(15)
	v_pk_fma_f32 v[20:21], v[20:21], v[130:131], v[226:227]
	v_pk_fma_f32 v[22:23], v[22:23], v[132:133], v[228:229]
	global_load_dwordx4 v[226:229], v[164:165], off offset:528 nt
	s_waitcnt vmcnt(15)
	v_pk_fma_f32 v[26:27], v[26:27], v[136:137], v[232:233]
	v_pk_fma_f32 v[24:25], v[24:25], v[134:135], v[230:231]
	global_load_dwordx4 v[230:233], v[164:165], off offset:512 nt
	s_waitcnt vmcnt(15)
	v_pk_fma_f32 v[90:91], v[90:91], v[140:141], v[236:237]
	v_pk_fma_f32 v[88:89], v[88:89], v[138:139], v[234:235]
	v_add_co_u32_e32 v164, vcc, 0x160000, v150
	s_nop 1
	v_addc_co_u32_e32 v165, vcc, 0, v151, vcc
	global_load_dwordx4 v[234:237], v[164:165], off nt
	s_waitcnt vmcnt(15)
	v_pk_fma_f32 v[94:95], v[94:95], v[144:145], v[240:241]
	v_pk_fma_f32 v[92:93], v[92:93], v[142:143], v[238:239]
	global_load_dwordx4 v[238:241], v[164:165], off offset:16 nt
	s_waitcnt vmcnt(15)
	v_pk_fma_f32 v[34:35], v[34:35], v[132:133], v[244:245]
	v_pk_fma_f32 v[32:33], v[32:33], v[130:131], v[242:243]
	global_load_dwordx4 v[242:245], v[164:165], off offset:528 nt
	s_waitcnt vmcnt(15)
	v_pk_fma_f32 v[42:43], v[42:43], v[136:137], v[156:157]
	v_pk_fma_f32 v[40:41], v[40:41], v[134:135], v[154:155]
	global_load_dwordx4 v[154:157], v[164:165], off offset:512 nt
	s_waitcnt vmcnt(15)
	v_pk_fma_f32 v[104:105], v[104:105], v[144:145], v[180:181]
	v_pk_fma_f32 v[102:103], v[102:103], v[142:143], v[178:179]
	s_waitcnt vmcnt(14)
	v_pk_fma_f32 v[100:101], v[100:101], v[140:141], v[184:185]
	v_pk_fma_f32 v[98:99], v[98:99], v[138:139], v[182:183]
	s_waitcnt vmcnt(13)
	v_pk_fma_f32 v[56:57], v[56:57], v[130:131], v[186:187]
	v_pk_fma_f32 v[58:59], v[58:59], v[132:133], v[188:189]
	s_waitcnt vmcnt(12)
	v_pk_fma_f32 v[62:63], v[62:63], v[136:137], v[192:193]
	v_pk_fma_f32 v[60:61], v[60:61], v[134:135], v[190:191]
	s_waitcnt vmcnt(11)
	v_pk_fma_f32 v[86:87], v[86:87], v[144:145], v[200:201]
	v_pk_fma_f32 v[84:85], v[84:85], v[142:143], v[198:199]
	s_waitcnt vmcnt(10)
	v_pk_fma_f32 v[82:83], v[82:83], v[140:141], v[204:205]
	v_pk_fma_f32 v[80:81], v[80:81], v[138:139], v[202:203]
	s_waitcnt vmcnt(9)
	v_pk_fma_f32 v[72:73], v[72:73], v[130:131], v[206:207]
	v_pk_fma_f32 v[74:75], v[74:75], v[132:133], v[208:209]
	s_waitcnt vmcnt(8)
	v_pk_fma_f32 v[78:79], v[78:79], v[136:137], v[216:217]
	v_pk_fma_f32 v[76:77], v[76:77], v[134:135], v[214:215]
	s_waitcnt vmcnt(7)
	v_pk_fma_f32 v[70:71], v[70:71], v[144:145], v[220:221]
	v_pk_fma_f32 v[68:69], v[68:69], v[142:143], v[218:219]
	s_waitcnt vmcnt(6)
	v_pk_fma_f32 v[66:67], v[66:67], v[140:141], v[224:225]
	v_pk_fma_f32 v[64:65], v[64:65], v[138:139], v[222:223]
	s_waitcnt vmcnt(5)
	v_pk_fma_f32 v[50:51], v[50:51], v[132:133], v[228:229]
	v_pk_fma_f32 v[48:49], v[48:49], v[130:131], v[226:227]
	s_waitcnt vmcnt(4)
	v_pk_fma_f32 v[54:55], v[54:55], v[136:137], v[232:233]
	v_pk_fma_f32 v[52:53], v[52:53], v[134:135], v[230:231]
	s_waitcnt vmcnt(3)
	v_pk_fma_f32 v[46:47], v[46:47], v[144:145], v[236:237]
	v_pk_fma_f32 v[44:45], v[44:45], v[142:143], v[234:235]
	s_waitcnt vmcnt(2)
	v_pk_fma_f32 v[38:39], v[38:39], v[140:141], v[240:241]
	v_pk_fma_f32 v[36:37], v[36:37], v[138:139], v[238:239]
	s_waitcnt vmcnt(1)
	v_pk_fma_f32 v[18:19], v[18:19], v[132:133], v[244:245]
	v_pk_fma_f32 v[16:17], v[16:17], v[130:131], v[242:243]
	s_waitcnt vmcnt(0)
	v_pk_fma_f32 v[28:29], v[28:29], v[134:135], v[154:155]
	v_pk_fma_f32 v[30:31], v[30:31], v[136:137], v[156:157]
	s_mov_b64 s[0:1], 0x160000
	s_lshl_b32 s0, s4, 2
	s_add_i32 s0, s0, 0
	v_cmp_eq_u32_e32 vcc, 0, v152
	v_mul_f32_e32 v132, v111, v111
	v_mul_f32_e32 v133, v113, v113
	v_fmac_f32_e32 v132, v110, v110
	v_fmac_f32_e32 v133, v112, v112
	v_add_f32_e32 v132, v132, v133
	v_mul_f32_e32 v133, v107, v107
	v_mul_f32_e32 v134, v109, v109
	v_fmac_f32_e32 v133, v106, v106
	v_fmac_f32_e32 v134, v108, v108
	v_add_f32_e32 v133, v133, v134
	v_add_f32_e32 v132, v132, v133
	v_mul_f32_e32 v133, v5, v5
	v_mul_f32_e32 v134, v7, v7
	v_fmac_f32_e32 v133, v4, v4
	v_fmac_f32_e32 v134, v6, v6
	v_add_f32_e32 v133, v133, v134
	v_add_f32_e32 v132, v133, v132
	v_mul_f32_e32 v133, v1, v1
	v_mul_f32_e32 v134, v3, v3
	v_fmac_f32_e32 v133, v0, v0
	v_fmac_f32_e32 v134, v2, v2
	v_mbcnt_lo_u32_b32 v96, -1, 0
	v_mbcnt_hi_u32_b32 v96, -1, v96
	v_add_f32_e32 v133, v133, v134
	v_lshlrev_b32_e32 v130, 2, v96
	v_xor_b32_e32 v131, 64, v130
	v_add_f32_e32 v132, v133, v132
	ds_bpermute_b32 v133, v131, v132
	v_xor_b32_e32 v130, 0x80, v130
	s_waitcnt lgkmcnt(0)
	v_add_f32_e32 v133, v132, v133
	ds_bpermute_b32 v134, v130, v133
	v_lshl_add_u32 v132, v172, 4, s0
	s_and_saveexec_b64 s[0:1], vcc
	s_cbranch_execz .LBB0_1002
	s_waitcnt lgkmcnt(0)
	v_add_f32_e32 v133, v133, v134
	ds_write_b32 v132, v133

.Lmy_pad2:
	global_load_dwordx4 v[178:181], v[150:151], off offset:16 nt
	global_load_dwordx4 v[182:185], v[150:151], off nt
	global_load_dwordx4 v[186:189], v[150:151], off offset:528 nt
	global_load_dwordx4 v[190:193], v[150:151], off offset:512 nt
	v_add_co_u32_e32 v164, vcc, 0x20000, v150
	s_nop 1
	v_addc_co_u32_e32 v165, vcc, 0, v151, vcc
	global_load_dwordx4 v[198:201], v[164:165], off offset:16 nt
	global_load_dwordx4 v[202:205], v[164:165], off nt
	global_load_dwordx4 v[206:209], v[164:165], off offset:528 nt
	global_load_dwordx4 v[214:217], v[164:165], off offset:512 nt
	v_add_co_u32_e32 v164, vcc, 0x40000, v150
	s_nop 1
	v_addc_co_u32_e32 v165, vcc, 0, v151, vcc
	global_load_dwordx4 v[218:221], v[164:165], off offset:16 nt
	global_load_dwordx4 v[222:225], v[164:165], off nt
	global_load_dwordx4 v[226:229], v[164:165], off offset:528 nt
	global_load_dwordx4 v[230:233], v[164:165], off offset:512 nt
	v_add_co_u32_e32 v164, vcc, 0x60000, v150
	s_nop 1
	v_addc_co_u32_e32 v165, vcc, 0, v151, vcc
	global_load_dwordx4 v[234:237], v[164:165], off offset:16 nt
	global_load_dwordx4 v[238:241], v[164:165], off nt
	global_load_dwordx4 v[242:245], v[164:165], off offset:528 nt
	global_load_dwordx4 v[154:157], v[164:165], off offset:512 nt
	s_waitcnt vmcnt(15)
	v_pk_fma_f32 v[108:109], v[108:109], v[140:141], v[180:181]
	v_pk_fma_f32 v[106:107], v[106:107], v[138:139], v[178:179]
	v_add_co_u32_e32 v164, vcc, 0x100000, v150
	s_nop 1
	v_addc_co_u32_e32 v165, vcc, 0, v151, vcc
	global_load_dwordx4 v[178:181], v[164:165], off nt
	s_waitcnt vmcnt(15)
	v_pk_fma_f32 v[112:113], v[112:113], v[144:145], v[184:185]
	v_pk_fma_f32 v[110:111], v[110:111], v[142:143], v[182:183]
	global_load_dwordx4 v[182:185], v[164:165], off offset:16 nt
	s_waitcnt vmcnt(15)
	v_pk_fma_f32 v[0:1], v[0:1], v[130:131], v[186:187]
	v_pk_fma_f32 v[2:3], v[2:3], v[132:133], v[188:189]
	global_load_dwordx4 v[186:189], v[164:165], off offset:528 nt
	s_waitcnt vmcnt(15)
	v_pk_fma_f32 v[6:7], v[6:7], v[136:137], v[192:193]
	v_pk_fma_f32 v[4:5], v[4:5], v[134:135], v[190:191]
	global_load_dwordx4 v[190:193], v[164:165], off offset:512 nt
	s_waitcnt vmcnt(15)
	v_pk_fma_f32 v[116:117], v[116:117], v[140:141], v[200:201]
	v_pk_fma_f32 v[114:115], v[114:115], v[138:139], v[198:199]
	v_add_co_u32_e32 v164, vcc, 0x120000, v150
	s_nop 1
	v_addc_co_u32_e32 v165, vcc, 0, v151, vcc
	global_load_dwordx4 v[198:201], v[164:165], off nt
	s_waitcnt vmcnt(15)
	v_pk_fma_f32 v[120:121], v[120:121], v[144:145], v[204:205]
	v_pk_fma_f32 v[118:119], v[118:119], v[142:143], v[202:203]
	global_load_dwordx4 v[202:205], v[164:165], off offset:16 nt
	s_waitcnt vmcnt(15)
	v_pk_fma_f32 v[8:9], v[8:9], v[130:131], v[206:207]
	v_pk_fma_f32 v[10:11], v[10:11], v[132:133], v[208:209]
	global_load_dwordx4 v[206:209], v[164:165], off offset:528 nt
	s_waitcnt vmcnt(15)
	v_pk_fma_f32 v[14:15], v[14:15], v[136:137], v[216:217]
	v_pk_fma_f32 v[12:13], v[12:13], v[134:135], v[214:215]
	global_load_dwordx4 v[214:217], v[164:165], off offset:512 nt
	s_waitcnt vmcnt(15)
	v_pk_fma_f32 v[124:125], v[124:125], v[140:141], v[220:221]
	v_pk_fma_f32 v[122:123], v[122:123], v[138:139], v[218:219]
	v_add_co_u32_e32 v164, vcc, 0x140000, v150
	s_nop 1
	v_addc_co_u32_e32 v165, vcc, 0, v151, vcc
	global_load_dwordx4 v[218:221], v[164:165], off nt
	s_waitcnt vmcnt(15)
	v_pk_fma_f32 v[128:129], v[128:129], v[144:145], v[224:225]
	v_pk_fma_f32 v[126:127], v[126:127], v[142:143], v[222:223]
	global_load_dwordx4 v[222:225], v[164:165], off offset:16 nt
	s_waitcnt vmcnt(15)
	v_pk_fma_f32 v[20:21], v[20:21], v[130:131], v[226:227]
	v_pk_fma_f32 v[22:23], v[22:23], v[132:133], v[228:229]
	global_load_dwordx4 v[226:229], v[164:165], off offset:528 nt
	s_waitcnt vmcnt(15)
	v_pk_fma_f32 v[26:27], v[26:27], v[136:137], v[232:233]
	v_pk_fma_f32 v[24:25], v[24:25], v[134:135], v[230:231]
	global_load_dwordx4 v[230:233], v[164:165], off offset:512 nt
	s_waitcnt vmcnt(15)
	v_pk_fma_f32 v[90:91], v[90:91], v[140:141], v[236:237]
	v_pk_fma_f32 v[88:89], v[88:89], v[138:139], v[234:235]
	v_add_co_u32_e32 v164, vcc, 0x160000, v150
	s_nop 1
	v_addc_co_u32_e32 v165, vcc, 0, v151, vcc
	global_load_dwordx4 v[234:237], v[164:165], off nt
	s_waitcnt vmcnt(15)
	v_pk_fma_f32 v[94:95], v[94:95], v[144:145], v[240:241]
	v_pk_fma_f32 v[92:93], v[92:93], v[142:143], v[238:239]
	global_load_dwordx4 v[238:241], v[164:165], off offset:16 nt
	s_waitcnt vmcnt(15)
	v_pk_fma_f32 v[38:39], v[38:39], v[132:133], v[244:245]
	v_pk_fma_f32 v[36:37], v[36:37], v[130:131], v[242:243]
	global_load_dwordx4 v[242:245], v[164:165], off offset:528 nt
	s_waitcnt vmcnt(15)
	v_pk_fma_f32 v[42:43], v[42:43], v[136:137], v[156:157]
	v_pk_fma_f32 v[40:41], v[40:41], v[134:135], v[154:155]
	global_load_dwordx4 v[154:157], v[164:165], off offset:512 nt
	s_waitcnt vmcnt(15)
	v_pk_fma_f32 v[104:105], v[104:105], v[144:145], v[180:181]
	v_pk_fma_f32 v[102:103], v[102:103], v[142:143], v[178:179]
	s_waitcnt vmcnt(14)
	v_pk_fma_f32 v[100:101], v[100:101], v[140:141], v[184:185]
	v_pk_fma_f32 v[98:99], v[98:99], v[138:139], v[182:183]
	s_waitcnt vmcnt(13)
	v_pk_fma_f32 v[56:57], v[56:57], v[130:131], v[186:187]
	v_pk_fma_f32 v[58:59], v[58:59], v[132:133], v[188:189]
	s_waitcnt vmcnt(12)
	v_pk_fma_f32 v[62:63], v[62:63], v[136:137], v[192:193]
	v_pk_fma_f32 v[60:61], v[60:61], v[134:135], v[190:191]
	s_waitcnt vmcnt(11)
	v_pk_fma_f32 v[86:87], v[86:87], v[144:145], v[200:201]
	v_pk_fma_f32 v[84:85], v[84:85], v[142:143], v[198:199]
	s_waitcnt vmcnt(10)
	v_pk_fma_f32 v[82:83], v[82:83], v[140:141], v[204:205]
	v_pk_fma_f32 v[80:81], v[80:81], v[138:139], v[202:203]
	s_waitcnt vmcnt(9)
	v_pk_fma_f32 v[72:73], v[72:73], v[130:131], v[206:207]
	v_pk_fma_f32 v[74:75], v[74:75], v[132:133], v[208:209]
	s_waitcnt vmcnt(8)
	v_pk_fma_f32 v[78:79], v[78:79], v[136:137], v[216:217]
	v_pk_fma_f32 v[76:77], v[76:77], v[134:135], v[214:215]
	s_waitcnt vmcnt(7)
	v_pk_fma_f32 v[70:71], v[70:71], v[144:145], v[220:221]
	v_pk_fma_f32 v[68:69], v[68:69], v[142:143], v[218:219]
	s_waitcnt vmcnt(6)
	v_pk_fma_f32 v[66:67], v[66:67], v[140:141], v[224:225]
	v_pk_fma_f32 v[64:65], v[64:65], v[138:139], v[222:223]
	s_waitcnt vmcnt(5)
	v_pk_fma_f32 v[50:51], v[50:51], v[132:133], v[228:229]
	v_pk_fma_f32 v[48:49], v[48:49], v[130:131], v[226:227]
	s_waitcnt vmcnt(4)
	v_pk_fma_f32 v[54:55], v[54:55], v[136:137], v[232:233]
	v_pk_fma_f32 v[52:53], v[52:53], v[134:135], v[230:231]
	s_waitcnt vmcnt(3)
	v_pk_fma_f32 v[46:47], v[46:47], v[144:145], v[236:237]
	v_pk_fma_f32 v[44:45], v[44:45], v[142:143], v[234:235]
	s_waitcnt vmcnt(2)
	v_pk_fma_f32 v[34:35], v[34:35], v[140:141], v[240:241]
	v_pk_fma_f32 v[32:33], v[32:33], v[138:139], v[238:239]
	s_waitcnt vmcnt(1)
	v_pk_fma_f32 v[18:19], v[18:19], v[132:133], v[244:245]
	v_pk_fma_f32 v[16:17], v[16:17], v[130:131], v[242:243]
	s_waitcnt vmcnt(0)
	v_pk_fma_f32 v[28:29], v[28:29], v[134:135], v[154:155]
	v_pk_fma_f32 v[30:31], v[30:31], v[136:137], v[156:157]
	s_mov_b64 s[0:1], 0x160000
	s_lshl_b32 s0, s4, 2
	s_add_i32 s0, s0, 0
	v_cmp_eq_u32_e32 vcc, 0, v152
	v_mul_f32_e32 v132, v111, v111
	v_mul_f32_e32 v133, v113, v113
	v_fmac_f32_e32 v132, v110, v110
	v_fmac_f32_e32 v133, v112, v112
	v_add_f32_e32 v132, v132, v133
	v_mul_f32_e32 v133, v107, v107
	v_mul_f32_e32 v134, v109, v109
	v_fmac_f32_e32 v133, v106, v106
	v_fmac_f32_e32 v134, v108, v108
	v_add_f32_e32 v133, v133, v134
	v_add_f32_e32 v132, v132, v133
	v_mul_f32_e32 v133, v5, v5
	v_mul_f32_e32 v134, v7, v7
	v_fmac_f32_e32 v133, v4, v4
	v_fmac_f32_e32 v134, v6, v6
	v_add_f32_e32 v133, v133, v134
	v_add_f32_e32 v132, v133, v132
	v_mul_f32_e32 v133, v1, v1
	v_mul_f32_e32 v134, v3, v3
	v_fmac_f32_e32 v133, v0, v0
	v_fmac_f32_e32 v134, v2, v2
	v_mbcnt_lo_u32_b32 v96, -1, 0
	v_mbcnt_hi_u32_b32 v96, -1, v96
	v_add_f32_e32 v133, v133, v134
	v_lshlrev_b32_e32 v130, 2, v96
	v_xor_b32_e32 v131, 64, v130
	v_add_f32_e32 v132, v133, v132
	ds_bpermute_b32 v133, v131, v132
	v_xor_b32_e32 v130, 0x80, v130
	s_waitcnt lgkmcnt(0)
	v_add_f32_e32 v133, v132, v133
	ds_bpermute_b32 v134, v130, v133
	v_lshl_add_u32 v132, v172, 4, s0
	s_and_saveexec_b64 s[0:1], vcc
	s_cbranch_execz .LBB0_1366
	s_waitcnt lgkmcnt(0)
	v_add_f32_e32 v133, v133, v134
	ds_write_b32 v132, v133
